# E20: E14 + grid barrier: non-leader workgroups poll the top-level generation word directly (skip the per-XCD generation hop)
# baseline (speedup 1.0000x reference)
; __device__ __forceinline__ unsigned xb_ld(unsigned* p)              { return __hip_atomic_load(p, __ATOMIC_RELAXED, __HIP_MEMORY_SCOPE_AGENT); }
; __device__ __forceinline__ unsigned xb_add(unsigned* p, unsigned v) { return __hip_atomic_fetch_add(p, v, __ATOMIC_RELAXED, __HIP_MEMORY_SCOPE_AGENT); }
; #define XB_SPIN(cond, bar) do { unsigned _sp = 0; while (cond) { __builtin_amdgcn_s_sleep(1); \
;     if ((++_sp & 255u) == 0u) { if (xb_ld(&(bar)[XB_TMO])) break; if (_sp > XB_SPIN_CAP) { atomicAdd(&(bar)[XB_TMO], 1u); break; } } } } while (0)
; __device__ __forceinline__ void xcd_barrier(const XcdBarrier& b) {
;     ...
;         const unsigned old = xb_add(&bar[XB_XSUB(bx)], 1u);
;         const unsigned gen = old / nloc;
;         if (old + 1u == (gen + 1u) * nloc) {
;             __builtin_amdgcn_fence(__ATOMIC_RELEASE, "agent");
;             asm volatile("s_waitcnt vmcnt(0)" ::: "memory");
;             const unsigned og = xb_add(&bar[XB_TOP], 1u);
;             const unsigned tg = og / nx;
;             if (og + 1u == (tg + 1u) * nx) xb_add(&bar[XB_TOPGEN], 1u);
;             else XB_SPIN(xb_ld(&bar[XB_TOPGEN]) == tg, bar);
;             __builtin_amdgcn_fence(__ATOMIC_ACQUIRE, "agent");
;             xb_add(&bar[XB_XGEN(bx)], 1u);
;             asm volatile("s_waitcnt vmcnt(0)" ::: "memory");
;         } else {
;             XB_SPIN(xb_ld(&bar[XB_XGEN(bx)]) == gen, bar);
.LBB0_141:
	s_lshl_b32 s3, s3, 6
	s_add_i32 s8, s3, 0x500
	s_mov_b32 s9, 0
	s_lshl_b64 s[6:7], s[8:9], 2
	s_add_u32 s6, s38, s6
	s_addc_u32 s7, s39, s7
	v_mov_b32_e32 v1, 1
	v_mov_b64_e32 v[6:7], s[6:7]
	flat_atomic_add v1, v[6:7], v1 sc0
	v_cvt_f32_u32_e32 v3, v4
	v_sub_u32_e32 v5, 0, v4
	v_rcp_iflag_f32_e32 v3, v3
	s_nop 0
	v_mul_f32_e32 v3, 0x4f7ffffe, v3
	v_cvt_u32_f32_e32 v3, v3
	v_mul_lo_u32 v5, v5, v3
	v_mul_hi_u32 v5, v3, v5
	v_add_u32_e32 v3, v3, v5
	s_waitcnt vmcnt(0) lgkmcnt(0)
	v_mul_hi_u32 v3, v1, v3
	v_mul_lo_u32 v5, v3, v4
	v_add_u32_e32 v6, 1, v1
	v_sub_u32_e32 v1, v1, v5
	v_add_u32_e32 v7, 1, v3
	v_cmp_ge_u32_e32 vcc, v1, v4
	v_sub_u32_e32 v5, v1, v4
	s_nop 0
	v_cndmask_b32_e32 v3, v3, v7, vcc
	v_cndmask_b32_e32 v1, v1, v5, vcc
	v_add_u32_e32 v5, 1, v3
	v_cmp_ge_u32_e32 vcc, v1, v4
	s_nop 1
	v_cndmask_b32_e32 v1, v3, v5, vcc
	v_mad_u64_u32 v[4:5], s[6:7], v4, v1, v[4:5]
	v_cmp_ne_u32_e32 vcc, v6, v4
	s_and_saveexec_b64 s[6:7], vcc
	s_xor_b64 s[6:7], exec, s[6:7]
	s_cbranch_execz .LBB0_154
	s_add_i32 s8, s3, 0x900
	s_lshl_b64 s[8:9], s[8:9], 2
	s_add_u32 s10, s38, 0x3500
	s_addc_u32 s11, s39, 0
	v_mov_b64_e32 v[2:3], s[10:11]
	flat_load_dword v2, v[2:3] sc1
	s_waitcnt vmcnt(0) lgkmcnt(0)
	v_cmp_eq_u32_e32 vcc, v2, v1
	s_and_saveexec_b64 s[8:9], vcc
	s_cbranch_execz .LBB0_153
	s_mov_b32 s26, 1
	s_mov_b64 s[12:13], 0
	s_branch .LBB0_145

; __device__ __forceinline__ unsigned xb_ld(unsigned* p)              { return __hip_atomic_load(p, __ATOMIC_RELAXED, __HIP_MEMORY_SCOPE_AGENT); }
; __device__ __forceinline__ unsigned xb_add(unsigned* p, unsigned v) { return __hip_atomic_fetch_add(p, v, __ATOMIC_RELAXED, __HIP_MEMORY_SCOPE_AGENT); }
; #define XB_SPIN(cond, bar) do { unsigned _sp = 0; while (cond) { __builtin_amdgcn_s_sleep(1); \
;     if ((++_sp & 255u) == 0u) { if (xb_ld(&(bar)[XB_TMO])) break; if (_sp > XB_SPIN_CAP) { atomicAdd(&(bar)[XB_TMO], 1u); break; } } } } while (0)
; __device__ __forceinline__ void xcd_barrier(const XcdBarrier& b) {
;     ...
;         const unsigned old = xb_add(&bar[XB_XSUB(bx)], 1u);
;         const unsigned gen = old / nloc;
;         if (old + 1u == (gen + 1u) * nloc) {
;             __builtin_amdgcn_fence(__ATOMIC_RELEASE, "agent");
;             asm volatile("s_waitcnt vmcnt(0)" ::: "memory");
;             const unsigned og = xb_add(&bar[XB_TOP], 1u);
;             const unsigned tg = og / nx;
;             if (og + 1u == (tg + 1u) * nx) xb_add(&bar[XB_TOPGEN], 1u);
;             else XB_SPIN(xb_ld(&bar[XB_TOPGEN]) == tg, bar);
;             __builtin_amdgcn_fence(__ATOMIC_ACQUIRE, "agent");
;             xb_add(&bar[XB_XGEN(bx)], 1u);
;             asm volatile("s_waitcnt vmcnt(0)" ::: "memory");
;         } else {
;             XB_SPIN(xb_ld(&bar[XB_XGEN(bx)]) == gen, bar);
.LBB0_802:
	s_lshl_b32 s26, s45, 6
	s_add_i32 s80, s26, 0x500
	s_lshl_b64 s[6:7], s[80:81], 2
	s_add_u32 s6, s40, s6
	s_addc_u32 s7, s41, s7
	v_mov_b64_e32 v[8:9], s[6:7]
	flat_atomic_add v5, v[8:9], v194 sc0
	v_cvt_f32_u32_e32 v3, v6
	v_sub_u32_e32 v7, 0, v6
	v_rcp_iflag_f32_e32 v3, v3
	s_nop 0
	v_mul_f32_e32 v3, 0x4f7ffffe, v3
	v_cvt_u32_f32_e32 v3, v3
	v_mul_lo_u32 v7, v7, v3
	v_mul_hi_u32 v7, v3, v7
	v_add_u32_e32 v3, v3, v7
	s_waitcnt vmcnt(0) lgkmcnt(0)
	v_mul_hi_u32 v3, v5, v3
	v_mul_lo_u32 v7, v3, v6
	v_sub_u32_e32 v7, v5, v7
	v_cmp_ge_u32_e32 vcc, v7, v6
	v_add_u32_e32 v8, 1, v3
	v_add_u32_e32 v5, 1, v5
	v_cndmask_b32_e32 v3, v3, v8, vcc
	v_sub_u32_e32 v8, v7, v6
	v_cndmask_b32_e32 v7, v7, v8, vcc
	v_cmp_ge_u32_e32 vcc, v7, v6
	v_add_u32_e32 v7, 1, v3
	s_nop 0
	v_cndmask_b32_e32 v3, v3, v7, vcc
	v_mad_u64_u32 v[6:7], s[6:7], v6, v3, v[6:7]
	v_cmp_ne_u32_e32 vcc, v5, v6
	s_and_saveexec_b64 s[6:7], vcc
	s_xor_b64 s[6:7], exec, s[6:7]
	s_cbranch_execz .LBB0_815
	s_add_i32 s80, s26, 0x900
	s_lshl_b64 s[8:9], s[80:81], 2
	s_add_u32 s10, s40, 0x3500
	s_addc_u32 s11, s41, 0
	v_mov_b64_e32 v[4:5], s[10:11]
	flat_load_dword v4, v[4:5] sc1
	s_waitcnt vmcnt(0) lgkmcnt(0)
	v_cmp_eq_u32_e32 vcc, v4, v3
	s_and_saveexec_b64 s[8:9], vcc
	s_cbranch_execz .LBB0_814
	s_mov_b32 s27, 1
	s_mov_b64 s[12:13], 0
	s_branch .LBB0_806

; __device__ __forceinline__ unsigned xb_ld(unsigned* p)              { return __hip_atomic_load(p, __ATOMIC_RELAXED, __HIP_MEMORY_SCOPE_AGENT); }
; __device__ __forceinline__ unsigned xb_add(unsigned* p, unsigned v) { return __hip_atomic_fetch_add(p, v, __ATOMIC_RELAXED, __HIP_MEMORY_SCOPE_AGENT); }
; #define XB_SPIN(cond, bar) do { unsigned _sp = 0; while (cond) { __builtin_amdgcn_s_sleep(1); \
;     if ((++_sp & 255u) == 0u) { if (xb_ld(&(bar)[XB_TMO])) break; if (_sp > XB_SPIN_CAP) { atomicAdd(&(bar)[XB_TMO], 1u); break; } } } } while (0)
; __device__ __forceinline__ void xcd_barrier(const XcdBarrier& b) {
;     ...
;         const unsigned old = xb_add(&bar[XB_XSUB(bx)], 1u);
;         const unsigned gen = old / nloc;
;         if (old + 1u == (gen + 1u) * nloc) {
;             __builtin_amdgcn_fence(__ATOMIC_RELEASE, "agent");
;             asm volatile("s_waitcnt vmcnt(0)" ::: "memory");
;             const unsigned og = xb_add(&bar[XB_TOP], 1u);
;             const unsigned tg = og / nx;
;             if (og + 1u == (tg + 1u) * nx) xb_add(&bar[XB_TOPGEN], 1u);
;             else XB_SPIN(xb_ld(&bar[XB_TOPGEN]) == tg, bar);
;             __builtin_amdgcn_fence(__ATOMIC_ACQUIRE, "agent");
;             xb_add(&bar[XB_XGEN(bx)], 1u);
;             asm volatile("s_waitcnt vmcnt(0)" ::: "memory");
;         } else {
;             XB_SPIN(xb_ld(&bar[XB_XGEN(bx)]) == gen, bar);
.LBB0_1545:
	s_lshl_b32 s28, s45, 6
	s_add_i32 s80, s28, 0x500
	s_lshl_b64 s[8:9], s[80:81], 2
	s_add_u32 s8, s74, s8
	s_addc_u32 s9, s75, s9
	v_mov_b64_e32 v[8:9], s[8:9]
	flat_atomic_add v5, v[8:9], v194 sc0
	v_cvt_f32_u32_e32 v3, v6
	v_sub_u32_e32 v7, 0, v6
	v_rcp_iflag_f32_e32 v3, v3
	s_nop 0
	v_mul_f32_e32 v3, 0x4f7ffffe, v3
	v_cvt_u32_f32_e32 v3, v3
	v_mul_lo_u32 v7, v7, v3
	v_mul_hi_u32 v7, v3, v7
	v_add_u32_e32 v3, v3, v7
	s_waitcnt vmcnt(0) lgkmcnt(0)
	v_mul_hi_u32 v3, v5, v3
	v_mul_lo_u32 v7, v3, v6
	v_sub_u32_e32 v7, v5, v7
	v_cmp_ge_u32_e32 vcc, v7, v6
	v_add_u32_e32 v8, 1, v3
	v_add_u32_e32 v5, 1, v5
	v_cndmask_b32_e32 v3, v3, v8, vcc
	v_sub_u32_e32 v8, v7, v6
	v_cndmask_b32_e32 v7, v7, v8, vcc
	v_cmp_ge_u32_e32 vcc, v7, v6
	v_add_u32_e32 v7, 1, v3
	s_nop 0
	v_cndmask_b32_e32 v3, v3, v7, vcc
	v_mad_u64_u32 v[6:7], s[8:9], v6, v3, v[6:7]
	v_cmp_ne_u32_e32 vcc, v5, v6
	s_and_saveexec_b64 s[8:9], vcc
	s_xor_b64 s[8:9], exec, s[8:9]
	s_cbranch_execz .LBB0_1558
	s_add_i32 s80, s28, 0x900
	s_lshl_b64 s[10:11], s[80:81], 2
	s_add_u32 s12, s74, 0x3500
	s_addc_u32 s13, s75, 0
	v_mov_b64_e32 v[4:5], s[12:13]
	flat_load_dword v4, v[4:5] sc1
	s_waitcnt vmcnt(0) lgkmcnt(0)
	v_cmp_eq_u32_e32 vcc, v4, v3
	s_and_saveexec_b64 s[10:11], vcc
	s_cbranch_execz .LBB0_1557
	s_mov_b32 s29, 1
	s_mov_b64 s[14:15], 0
	s_branch .LBB0_1549

; __device__ __forceinline__ unsigned xb_ld(unsigned* p)              { return __hip_atomic_load(p, __ATOMIC_RELAXED, __HIP_MEMORY_SCOPE_AGENT); }
; __device__ __forceinline__ unsigned xb_add(unsigned* p, unsigned v) { return __hip_atomic_fetch_add(p, v, __ATOMIC_RELAXED, __HIP_MEMORY_SCOPE_AGENT); }
; #define XB_SPIN(cond, bar) do { unsigned _sp = 0; while (cond) { __builtin_amdgcn_s_sleep(1); \
;     if ((++_sp & 255u) == 0u) { if (xb_ld(&(bar)[XB_TMO])) break; if (_sp > XB_SPIN_CAP) { atomicAdd(&(bar)[XB_TMO], 1u); break; } } } } while (0)
; __device__ __forceinline__ void xcd_barrier(const XcdBarrier& b) {
;     ...
;         const unsigned old = xb_add(&bar[XB_XSUB(bx)], 1u);
;         const unsigned gen = old / nloc;
;         if (old + 1u == (gen + 1u) * nloc) {
;             __builtin_amdgcn_fence(__ATOMIC_RELEASE, "agent");
;             asm volatile("s_waitcnt vmcnt(0)" ::: "memory");
;             const unsigned og = xb_add(&bar[XB_TOP], 1u);
;             const unsigned tg = og / nx;
;             if (og + 1u == (tg + 1u) * nx) xb_add(&bar[XB_TOPGEN], 1u);
;             else XB_SPIN(xb_ld(&bar[XB_TOPGEN]) == tg, bar);
;             __builtin_amdgcn_fence(__ATOMIC_ACQUIRE, "agent");
;             xb_add(&bar[XB_XGEN(bx)], 1u);
;             asm volatile("s_waitcnt vmcnt(0)" ::: "memory");
;         } else {
;             XB_SPIN(xb_ld(&bar[XB_XGEN(bx)]) == gen, bar);
.LBB0_1695:
	s_lshl_b32 s30, s45, 6
	s_add_i32 s80, s30, 0x500
	s_lshl_b64 s[10:11], s[80:81], 2
	s_add_u32 s10, s76, s10
	s_addc_u32 s11, s77, s11
	v_mov_b64_e32 v[8:9], s[10:11]
	flat_atomic_add v5, v[8:9], v194 sc0
	v_cvt_f32_u32_e32 v3, v6
	v_sub_u32_e32 v7, 0, v6
	v_rcp_iflag_f32_e32 v3, v3
	s_nop 0
	v_mul_f32_e32 v3, 0x4f7ffffe, v3
	v_cvt_u32_f32_e32 v3, v3
	v_mul_lo_u32 v7, v7, v3
	v_mul_hi_u32 v7, v3, v7
	v_add_u32_e32 v3, v3, v7
	s_waitcnt vmcnt(0) lgkmcnt(0)
	v_mul_hi_u32 v3, v5, v3
	v_mul_lo_u32 v7, v3, v6
	v_sub_u32_e32 v7, v5, v7
	v_cmp_ge_u32_e32 vcc, v7, v6
	v_add_u32_e32 v8, 1, v3
	v_add_u32_e32 v5, 1, v5
	v_cndmask_b32_e32 v3, v3, v8, vcc
	v_sub_u32_e32 v8, v7, v6
	v_cndmask_b32_e32 v7, v7, v8, vcc
	v_cmp_ge_u32_e32 vcc, v7, v6
	v_add_u32_e32 v7, 1, v3
	s_nop 0
	v_cndmask_b32_e32 v3, v3, v7, vcc
	v_mad_u64_u32 v[6:7], s[10:11], v6, v3, v[6:7]
	v_cmp_ne_u32_e32 vcc, v5, v6
	s_and_saveexec_b64 s[10:11], vcc
	s_xor_b64 s[10:11], exec, s[10:11]
	s_cbranch_execz .LBB0_1708
	s_add_i32 s80, s30, 0x900
	s_lshl_b64 s[12:13], s[80:81], 2
	s_add_u32 s14, s76, 0x3500
	s_addc_u32 s15, s77, 0
	v_mov_b64_e32 v[4:5], s[14:15]
	flat_load_dword v4, v[4:5] sc1
	s_waitcnt vmcnt(0) lgkmcnt(0)
	v_cmp_eq_u32_e32 vcc, v4, v3
	s_and_saveexec_b64 s[12:13], vcc
	s_cbranch_execz .LBB0_1707
	s_mov_b32 s31, 1
	s_mov_b64 s[16:17], 0
	s_branch .LBB0_1699

; __device__ __forceinline__ unsigned xb_ld(unsigned* p)              { return __hip_atomic_load(p, __ATOMIC_RELAXED, __HIP_MEMORY_SCOPE_AGENT); }
; __device__ __forceinline__ unsigned xb_add(unsigned* p, unsigned v) { return __hip_atomic_fetch_add(p, v, __ATOMIC_RELAXED, __HIP_MEMORY_SCOPE_AGENT); }
; #define XB_SPIN(cond, bar) do { unsigned _sp = 0; while (cond) { __builtin_amdgcn_s_sleep(1); \
;     if ((++_sp & 255u) == 0u) { if (xb_ld(&(bar)[XB_TMO])) break; if (_sp > XB_SPIN_CAP) { atomicAdd(&(bar)[XB_TMO], 1u); break; } } } } while (0)
; __device__ __forceinline__ void xcd_barrier(const XcdBarrier& b) {
;     ...
;         const unsigned old = xb_add(&bar[XB_XSUB(bx)], 1u);
;         const unsigned gen = old / nloc;
;         if (old + 1u == (gen + 1u) * nloc) {
;             __builtin_amdgcn_fence(__ATOMIC_RELEASE, "agent");
;             asm volatile("s_waitcnt vmcnt(0)" ::: "memory");
;             const unsigned og = xb_add(&bar[XB_TOP], 1u);
;             const unsigned tg = og / nx;
;             if (og + 1u == (tg + 1u) * nx) xb_add(&bar[XB_TOPGEN], 1u);
;             else XB_SPIN(xb_ld(&bar[XB_TOPGEN]) == tg, bar);
;             __builtin_amdgcn_fence(__ATOMIC_ACQUIRE, "agent");
;             xb_add(&bar[XB_XGEN(bx)], 1u);
;             asm volatile("s_waitcnt vmcnt(0)" ::: "memory");
;         } else {
;             XB_SPIN(xb_ld(&bar[XB_XGEN(bx)]) == gen, bar);
.LBB0_1780:
	s_lshl_b32 s30, s45, 6
	s_add_i32 s80, s30, 0x500
	s_lshl_b64 s[10:11], s[80:81], 2
	s_add_u32 s10, s74, s10
	s_addc_u32 s11, s75, s11
	v_mov_b64_e32 v[8:9], s[10:11]
	flat_atomic_add v5, v[8:9], v194 sc0
	v_cvt_f32_u32_e32 v3, v6
	v_sub_u32_e32 v7, 0, v6
	v_rcp_iflag_f32_e32 v3, v3
	s_nop 0
	v_mul_f32_e32 v3, 0x4f7ffffe, v3
	v_cvt_u32_f32_e32 v3, v3
	v_mul_lo_u32 v7, v7, v3
	v_mul_hi_u32 v7, v3, v7
	v_add_u32_e32 v3, v3, v7
	s_waitcnt vmcnt(0) lgkmcnt(0)
	v_mul_hi_u32 v3, v5, v3
	v_mul_lo_u32 v7, v3, v6
	v_sub_u32_e32 v7, v5, v7
	v_cmp_ge_u32_e32 vcc, v7, v6
	v_add_u32_e32 v8, 1, v3
	v_add_u32_e32 v5, 1, v5
	v_cndmask_b32_e32 v3, v3, v8, vcc
	v_sub_u32_e32 v8, v7, v6
	v_cndmask_b32_e32 v7, v7, v8, vcc
	v_cmp_ge_u32_e32 vcc, v7, v6
	v_add_u32_e32 v7, 1, v3
	s_nop 0
	v_cndmask_b32_e32 v3, v3, v7, vcc
	v_mad_u64_u32 v[6:7], s[10:11], v6, v3, v[6:7]
	v_cmp_ne_u32_e32 vcc, v5, v6
	s_and_saveexec_b64 s[10:11], vcc
	s_xor_b64 s[10:11], exec, s[10:11]
	s_cbranch_execz .LBB0_1793
	s_add_i32 s80, s30, 0x900
	s_lshl_b64 s[12:13], s[80:81], 2
	s_add_u32 s14, s74, 0x3500
	s_addc_u32 s15, s75, 0
	v_mov_b64_e32 v[4:5], s[14:15]
	flat_load_dword v4, v[4:5] sc1
	s_waitcnt vmcnt(0) lgkmcnt(0)
	v_cmp_eq_u32_e32 vcc, v4, v3
	s_and_saveexec_b64 s[12:13], vcc
	s_cbranch_execz .LBB0_1792
	s_mov_b32 s31, 1
	s_mov_b64 s[16:17], 0
	s_branch .LBB0_1784

; __device__ __forceinline__ unsigned xb_ld(unsigned* p)              { return __hip_atomic_load(p, __ATOMIC_RELAXED, __HIP_MEMORY_SCOPE_AGENT); }
; __device__ __forceinline__ unsigned xb_add(unsigned* p, unsigned v) { return __hip_atomic_fetch_add(p, v, __ATOMIC_RELAXED, __HIP_MEMORY_SCOPE_AGENT); }
; #define XB_SPIN(cond, bar) do { unsigned _sp = 0; while (cond) { __builtin_amdgcn_s_sleep(1); \
;     if ((++_sp & 255u) == 0u) { if (xb_ld(&(bar)[XB_TMO])) break; if (_sp > XB_SPIN_CAP) { atomicAdd(&(bar)[XB_TMO], 1u); break; } } } } while (0)
; __device__ __forceinline__ void xcd_barrier(const XcdBarrier& b) {
;     ...
;         const unsigned old = xb_add(&bar[XB_XSUB(bx)], 1u);
;         const unsigned gen = old / nloc;
;         if (old + 1u == (gen + 1u) * nloc) {
;             __builtin_amdgcn_fence(__ATOMIC_RELEASE, "agent");
;             asm volatile("s_waitcnt vmcnt(0)" ::: "memory");
;             const unsigned og = xb_add(&bar[XB_TOP], 1u);
;             const unsigned tg = og / nx;
;             if (og + 1u == (tg + 1u) * nx) xb_add(&bar[XB_TOPGEN], 1u);
;             else XB_SPIN(xb_ld(&bar[XB_TOPGEN]) == tg, bar);
;             __builtin_amdgcn_fence(__ATOMIC_ACQUIRE, "agent");
;             xb_add(&bar[XB_XGEN(bx)], 1u);
;             asm volatile("s_waitcnt vmcnt(0)" ::: "memory");
;         } else {
;             XB_SPIN(xb_ld(&bar[XB_XGEN(bx)]) == gen, bar);
.LBB0_2051:
	s_lshl_b32 s28, s44, 6
	s_add_i32 s80, s28, 0x500
	s_lshl_b64 s[8:9], s[80:81], 2
	s_add_u32 s8, s40, s8
	s_addc_u32 s9, s41, s9
	v_mov_b64_e32 v[8:9], s[8:9]
	flat_atomic_add v5, v[8:9], v194 sc0
	v_cvt_f32_u32_e32 v3, v6
	v_sub_u32_e32 v7, 0, v6
	v_rcp_iflag_f32_e32 v3, v3
	s_nop 0
	v_mul_f32_e32 v3, 0x4f7ffffe, v3
	v_cvt_u32_f32_e32 v3, v3
	v_mul_lo_u32 v7, v7, v3
	v_mul_hi_u32 v7, v3, v7
	v_add_u32_e32 v3, v3, v7
	s_waitcnt vmcnt(0) lgkmcnt(0)
	v_mul_hi_u32 v3, v5, v3
	v_mul_lo_u32 v7, v3, v6
	v_sub_u32_e32 v7, v5, v7
	v_cmp_ge_u32_e32 vcc, v7, v6
	v_add_u32_e32 v8, 1, v3
	v_add_u32_e32 v5, 1, v5
	v_cndmask_b32_e32 v3, v3, v8, vcc
	v_sub_u32_e32 v8, v7, v6
	v_cndmask_b32_e32 v7, v7, v8, vcc
	v_cmp_ge_u32_e32 vcc, v7, v6
	v_add_u32_e32 v7, 1, v3
	s_nop 0
	v_cndmask_b32_e32 v3, v3, v7, vcc
	v_mad_u64_u32 v[6:7], s[8:9], v6, v3, v[6:7]
	v_cmp_ne_u32_e32 vcc, v5, v6
	s_and_saveexec_b64 s[8:9], vcc
	s_xor_b64 s[8:9], exec, s[8:9]
	v_readlane_b32 s44, v255, 28
	v_readlane_b32 s45, v255, 29
	s_cbranch_execz .LBB0_2064
	s_add_i32 s80, s28, 0x900
	s_lshl_b64 s[10:11], s[80:81], 2
	s_add_u32 s12, s40, 0x3500
	s_addc_u32 s13, s41, 0
	v_mov_b64_e32 v[4:5], s[12:13]
	flat_load_dword v4, v[4:5] sc1
	s_waitcnt vmcnt(0) lgkmcnt(0)
	v_cmp_eq_u32_e32 vcc, v4, v3
	s_and_saveexec_b64 s[10:11], vcc
	s_cbranch_execz .LBB0_2063
	s_mov_b32 s29, 1
	s_mov_b64 s[14:15], 0
	s_branch .LBB0_2055

; __device__ __forceinline__ unsigned xb_ld(unsigned* p)              { return __hip_atomic_load(p, __ATOMIC_RELAXED, __HIP_MEMORY_SCOPE_AGENT); }
; __device__ __forceinline__ unsigned xb_add(unsigned* p, unsigned v) { return __hip_atomic_fetch_add(p, v, __ATOMIC_RELAXED, __HIP_MEMORY_SCOPE_AGENT); }
; #define XB_SPIN(cond, bar) do { unsigned _sp = 0; while (cond) { __builtin_amdgcn_s_sleep(1); \
;     if ((++_sp & 255u) == 0u) { if (xb_ld(&(bar)[XB_TMO])) break; if (_sp > XB_SPIN_CAP) { atomicAdd(&(bar)[XB_TMO], 1u); break; } } } } while (0)
; __device__ __forceinline__ void xcd_barrier(const XcdBarrier& b) {
;     ...
;         const unsigned old = xb_add(&bar[XB_XSUB(bx)], 1u);
;         const unsigned gen = old / nloc;
;         if (old + 1u == (gen + 1u) * nloc) {
;             __builtin_amdgcn_fence(__ATOMIC_RELEASE, "agent");
;             asm volatile("s_waitcnt vmcnt(0)" ::: "memory");
;             const unsigned og = xb_add(&bar[XB_TOP], 1u);
;             const unsigned tg = og / nx;
;             if (og + 1u == (tg + 1u) * nx) xb_add(&bar[XB_TOPGEN], 1u);
;             else XB_SPIN(xb_ld(&bar[XB_TOPGEN]) == tg, bar);
;             __builtin_amdgcn_fence(__ATOMIC_ACQUIRE, "agent");
;             xb_add(&bar[XB_XGEN(bx)], 1u);
;             asm volatile("s_waitcnt vmcnt(0)" ::: "memory");
;         } else {
;             XB_SPIN(xb_ld(&bar[XB_XGEN(bx)]) == gen, bar);
.LBB0_2100:
	s_lshl_b32 s26, s44, 6
	s_add_i32 s80, s26, 0x500
	s_lshl_b64 s[6:7], s[80:81], 2
	s_add_u32 s6, s40, s6
	s_addc_u32 s7, s41, s7
	v_mov_b64_e32 v[8:9], s[6:7]
	flat_atomic_add v5, v[8:9], v194 sc0
	v_cvt_f32_u32_e32 v3, v6
	v_sub_u32_e32 v7, 0, v6
	v_rcp_iflag_f32_e32 v3, v3
	s_nop 0
	v_mul_f32_e32 v3, 0x4f7ffffe, v3
	v_cvt_u32_f32_e32 v3, v3
	v_mul_lo_u32 v7, v7, v3
	v_mul_hi_u32 v7, v3, v7
	v_add_u32_e32 v3, v3, v7
	s_waitcnt vmcnt(0) lgkmcnt(0)
	v_mul_hi_u32 v3, v5, v3
	v_mul_lo_u32 v7, v3, v6
	v_sub_u32_e32 v7, v5, v7
	v_cmp_ge_u32_e32 vcc, v7, v6
	v_add_u32_e32 v8, 1, v3
	v_add_u32_e32 v5, 1, v5
	v_cndmask_b32_e32 v3, v3, v8, vcc
	v_sub_u32_e32 v8, v7, v6
	v_cndmask_b32_e32 v7, v7, v8, vcc
	v_cmp_ge_u32_e32 vcc, v7, v6
	v_add_u32_e32 v7, 1, v3
	s_nop 0
	v_cndmask_b32_e32 v3, v3, v7, vcc
	v_mad_u64_u32 v[6:7], s[6:7], v6, v3, v[6:7]
	v_cmp_ne_u32_e32 vcc, v5, v6
	s_and_saveexec_b64 s[6:7], vcc
	s_xor_b64 s[6:7], exec, s[6:7]
	v_readlane_b32 s44, v255, 28
	v_readlane_b32 s45, v255, 29
	s_cbranch_execz .LBB0_2113
	s_add_i32 s80, s26, 0x900
	s_lshl_b64 s[8:9], s[80:81], 2
	s_add_u32 s10, s40, 0x3500
	s_addc_u32 s11, s41, 0
	v_mov_b64_e32 v[4:5], s[10:11]
	flat_load_dword v4, v[4:5] sc1
	s_waitcnt vmcnt(0) lgkmcnt(0)
	v_cmp_eq_u32_e32 vcc, v4, v3
	s_and_saveexec_b64 s[8:9], vcc
	s_cbranch_execz .LBB0_2112
	s_mov_b32 s27, 1
	s_mov_b64 s[12:13], 0
	s_branch .LBB0_2104
